# p1_kern inner loop: 16 p per load round trip instead of 1 (same arithmetic)
# speedup vs baseline: 1.0045x; 1.0045x over previous
.LBB0_34:
	v_lshl_add_u64 v[26:27], s[78:79], 0, v[8:9]
	v_add_co_u32_e32 v26, vcc, 0xdc00000, v26
	v_lshl_add_u64 v[22:23], v[12:13], 0, s[8:9]
	s_nop 0
	v_addc_co_u32_e32 v27, vcc, 0, v27, vcc
	v_lshl_add_u64 v[28:29], s[78:79], 0, v[6:7]
	v_lshl_add_u64 v[18:19], v[10:11], 0, s[8:9]
	v_add_co_u32_e32 v28, vcc, 0xdd00000, v28
	s_nop 1
	v_addc_co_u32_e32 v29, vcc, 0, v29, vcc
	global_load_dwordx4 v[40:43], v[22:23], off offset:0
	global_load_dwordx4 v[44:47], v[22:23], off offset:16
	global_load_dwordx4 v[48:51], v[22:23], off offset:32
	global_load_dwordx4 v[52:55], v[22:23], off offset:48
	global_load_dwordx4 v[56:59], v[18:19], off offset:0
	global_load_dwordx4 v[60:63], v[18:19], off offset:16
	global_load_dwordx4 v[64:67], v[18:19], off offset:32
	global_load_dwordx4 v[68:71], v[18:19], off offset:48
	global_load_dwordx2 v[72:73], v[26:27], off offset:0
	global_load_dwordx2 v[74:75], v[26:27], off offset:136
	global_load_dwordx2 v[76:77], v[26:27], off offset:272
	global_load_dwordx2 v[78:79], v[26:27], off offset:408
	global_load_dwordx2 v[80:81], v[26:27], off offset:544
	global_load_dwordx2 v[82:83], v[26:27], off offset:680
	global_load_dwordx2 v[84:85], v[26:27], off offset:816
	global_load_dwordx2 v[86:87], v[26:27], off offset:952
	global_load_dwordx2 v[88:89], v[26:27], off offset:1088
	global_load_dwordx2 v[90:91], v[26:27], off offset:1224
	global_load_dwordx2 v[92:93], v[26:27], off offset:1360
	global_load_dwordx2 v[94:95], v[26:27], off offset:1496
	global_load_dwordx2 v[96:97], v[26:27], off offset:1632
	global_load_dwordx2 v[98:99], v[26:27], off offset:1768
	global_load_dwordx2 v[100:101], v[26:27], off offset:1904
	global_load_dwordx2 v[102:103], v[26:27], off offset:2040
	global_load_dwordx2 v[104:105], v[28:29], off offset:0
	global_load_dwordx2 v[106:107], v[28:29], off offset:128
	global_load_dwordx2 v[108:109], v[28:29], off offset:256
	global_load_dwordx2 v[110:111], v[28:29], off offset:384
	global_load_dwordx2 v[112:113], v[28:29], off offset:512
	global_load_dwordx2 v[114:115], v[28:29], off offset:640
	global_load_dwordx2 v[116:117], v[28:29], off offset:768
	global_load_dwordx2 v[118:119], v[28:29], off offset:896
	global_load_dwordx2 v[120:121], v[28:29], off offset:1024
	global_load_dwordx2 v[122:123], v[28:29], off offset:1152
	global_load_dwordx2 v[124:125], v[28:29], off offset:1280
	global_load_dwordx2 v[126:127], v[28:29], off offset:1408
	global_load_dwordx2 v[128:129], v[28:29], off offset:1536
	global_load_dwordx2 v[130:131], v[28:29], off offset:1664
	global_load_dwordx2 v[132:133], v[28:29], off offset:1792
	global_load_dwordx2 v[134:135], v[28:29], off offset:1920
	s_add_u32 s8, s8, 64
	s_addc_u32 s9, s9, 0
	s_mov_b64 s[10:11], 0x800
	v_lshl_add_u64 v[6:7], v[6:7], 0, s[10:11]
	s_mov_b64 s[10:11], 0x880
	v_lshl_add_u64 v[8:9], v[8:9], 0, s[10:11]
	s_cmpk_eq_i32 s8, 0x100
	s_waitcnt vmcnt(0)
	v_mul_f32_e32 v136, v73, v40
	v_mul_f32_e32 v137, v72, v40
	v_fma_f32 v138, v72, v56, -v136
	v_fma_f32 v139, v73, v56, v137
	v_mul_f32_e32 v140, v104, v138
	v_mul_f32_e32 v141, v105, v139
	v_sub_f32_e32 v140, v140, v141
	v_add_f32_e32 v16, v16, v140
	v_mul_f32_e32 v136, v75, v41
	v_mul_f32_e32 v137, v74, v41
	v_fma_f32 v138, v74, v57, -v136
	v_fma_f32 v139, v75, v57, v137
	v_mul_f32_e32 v140, v106, v138
	v_mul_f32_e32 v141, v107, v139
	v_sub_f32_e32 v140, v140, v141
	v_add_f32_e32 v16, v16, v140
	v_mul_f32_e32 v136, v77, v42
	v_mul_f32_e32 v137, v76, v42
	v_fma_f32 v138, v76, v58, -v136
	v_fma_f32 v139, v77, v58, v137
	v_mul_f32_e32 v140, v108, v138
	v_mul_f32_e32 v141, v109, v139
	v_sub_f32_e32 v140, v140, v141
	v_add_f32_e32 v16, v16, v140
	v_mul_f32_e32 v136, v79, v43
	v_mul_f32_e32 v137, v78, v43
	v_fma_f32 v138, v78, v59, -v136
	v_fma_f32 v139, v79, v59, v137
	v_mul_f32_e32 v140, v110, v138
	v_mul_f32_e32 v141, v111, v139
	v_sub_f32_e32 v140, v140, v141
	v_add_f32_e32 v16, v16, v140
	v_mul_f32_e32 v136, v81, v44
	v_mul_f32_e32 v137, v80, v44
	v_fma_f32 v138, v80, v60, -v136
	v_fma_f32 v139, v81, v60, v137
	v_mul_f32_e32 v140, v112, v138
	v_mul_f32_e32 v141, v113, v139
	v_sub_f32_e32 v140, v140, v141
	v_add_f32_e32 v16, v16, v140
	v_mul_f32_e32 v136, v83, v45
	v_mul_f32_e32 v137, v82, v45
	v_fma_f32 v138, v82, v61, -v136
	v_fma_f32 v139, v83, v61, v137
	v_mul_f32_e32 v140, v114, v138
	v_mul_f32_e32 v141, v115, v139
	v_sub_f32_e32 v140, v140, v141
	v_add_f32_e32 v16, v16, v140
	v_mul_f32_e32 v136, v85, v46
	v_mul_f32_e32 v137, v84, v46
	v_fma_f32 v138, v84, v62, -v136
	v_fma_f32 v139, v85, v62, v137
	v_mul_f32_e32 v140, v116, v138
	v_mul_f32_e32 v141, v117, v139
	v_sub_f32_e32 v140, v140, v141
	v_add_f32_e32 v16, v16, v140
	v_mul_f32_e32 v136, v87, v47
	v_mul_f32_e32 v137, v86, v47
	v_fma_f32 v138, v86, v63, -v136
	v_fma_f32 v139, v87, v63, v137
	v_mul_f32_e32 v140, v118, v138
	v_mul_f32_e32 v141, v119, v139
	v_sub_f32_e32 v140, v140, v141
	v_add_f32_e32 v16, v16, v140
	v_mul_f32_e32 v136, v89, v48
	v_mul_f32_e32 v137, v88, v48
	v_fma_f32 v138, v88, v64, -v136
	v_fma_f32 v139, v89, v64, v137
	v_mul_f32_e32 v140, v120, v138
	v_mul_f32_e32 v141, v121, v139
	v_sub_f32_e32 v140, v140, v141
	v_add_f32_e32 v16, v16, v140
	v_mul_f32_e32 v136, v91, v49
	v_mul_f32_e32 v137, v90, v49
	v_fma_f32 v138, v90, v65, -v136
	v_fma_f32 v139, v91, v65, v137
	v_mul_f32_e32 v140, v122, v138
	v_mul_f32_e32 v141, v123, v139
	v_sub_f32_e32 v140, v140, v141
	v_add_f32_e32 v16, v16, v140
	v_mul_f32_e32 v136, v93, v50
	v_mul_f32_e32 v137, v92, v50
	v_fma_f32 v138, v92, v66, -v136
	v_fma_f32 v139, v93, v66, v137
	v_mul_f32_e32 v140, v124, v138
	v_mul_f32_e32 v141, v125, v139
	v_sub_f32_e32 v140, v140, v141
	v_add_f32_e32 v16, v16, v140
	v_mul_f32_e32 v136, v95, v51
	v_mul_f32_e32 v137, v94, v51
	v_fma_f32 v138, v94, v67, -v136
	v_fma_f32 v139, v95, v67, v137
	v_mul_f32_e32 v140, v126, v138
	v_mul_f32_e32 v141, v127, v139
	v_sub_f32_e32 v140, v140, v141
	v_add_f32_e32 v16, v16, v140
	v_mul_f32_e32 v136, v97, v52
	v_mul_f32_e32 v137, v96, v52
	v_fma_f32 v138, v96, v68, -v136
	v_fma_f32 v139, v97, v68, v137
	v_mul_f32_e32 v140, v128, v138
	v_mul_f32_e32 v141, v129, v139
	v_sub_f32_e32 v140, v140, v141
	v_add_f32_e32 v16, v16, v140
	v_mul_f32_e32 v136, v99, v53
	v_mul_f32_e32 v137, v98, v53
	v_fma_f32 v138, v98, v69, -v136
	v_fma_f32 v139, v99, v69, v137
	v_mul_f32_e32 v140, v130, v138
	v_mul_f32_e32 v141, v131, v139
	v_sub_f32_e32 v140, v140, v141
	v_add_f32_e32 v16, v16, v140
	v_mul_f32_e32 v136, v101, v54
	v_mul_f32_e32 v137, v100, v54
	v_fma_f32 v138, v100, v70, -v136
	v_fma_f32 v139, v101, v70, v137
	v_mul_f32_e32 v140, v132, v138
	v_mul_f32_e32 v141, v133, v139
	v_sub_f32_e32 v140, v140, v141
	v_add_f32_e32 v16, v16, v140
	v_mul_f32_e32 v136, v103, v55
	v_mul_f32_e32 v137, v102, v55
	v_fma_f32 v138, v102, v71, -v136
	v_fma_f32 v139, v103, v71, v137
	v_mul_f32_e32 v140, v134, v138
	v_mul_f32_e32 v141, v135, v139
	v_sub_f32_e32 v140, v140, v141
	v_add_f32_e32 v16, v16, v140
	s_cbranch_scc0 .LBB0_34
	v_ashrrev_i32_e32 v5, 31, v4
	v_lshl_add_u64 v[6:7], v[4:5], 2, s[20:21]
	v_add_u32_e32 v4, s28, v4
	s_mov_b32 s8, 0x3ffff
	v_cmp_lt_i32_e32 vcc, s8, v4
	v_add_u32_e32 v14, s17, v14
	s_or_b64 s[6:7], vcc, s[6:7]
	v_add_u32_e32 v15, s22, v15
	global_store_dword v[6:7], v16, off
	s_andn2_b64 exec, exec, s[6:7]
	s_cbranch_execnz .LBB0_33
